# FoX max by permlane32 swap, DSA denominators and compaction scan by DPP, next-batch gather issued per 16-key group as registers free up
# speedup vs baseline: 1.0387x; 1.0008x over previous
;     ...
;           int c = 0;
; #pragma unroll
;           for (int rb = 0; rb < 8; ++rb) { if (rb * 8 < nreg) {
; #pragma unroll
;               for (int r = rb * 8; r < rb * 8 + 8; ++r) c += (u[r] >= T) ? 1 : 0; } }
;           int incl = c;
; #pragma unroll
;           for (int o = 1; o < 64; o <<= 1) { const int y = __shfl_up(incl, o); if (lane >= o) incl += y; }
;           int off = incl - c;
; #pragma unroll
;           for (int rb = 0; rb < 8; ++rb) { if (rb * 8 < nreg) {
; #pragma unroll
;               for (int r = rb * 8; r < rb * 8 + 8; ++r) { const bool sel = u[r] >= T; list[sel ? off : 256 + lane] = (u16)(r * 64 + lane); off += sel ? 1 : 0; } } }
.LBB0_908:
	v_mov_b32_e32 v73, v70
	s_nop 1
	v_add_u32_dpp v73, v73, v73 row_shr:1 row_mask:0xf bank_mask:0xf bound_ctrl:0
	s_nop 1
	v_add_u32_dpp v73, v73, v73 row_shr:2 row_mask:0xf bank_mask:0xf bound_ctrl:0
	s_nop 1
	v_add_u32_dpp v73, v73, v73 row_shr:4 row_mask:0xf bank_mask:0xf bound_ctrl:0
	s_nop 1
	v_add_u32_dpp v73, v73, v73 row_shr:8 row_mask:0xf bank_mask:0xf bound_ctrl:0
	s_nop 1
	v_add_u32_dpp v73, v73, v73 row_bcast:15 row_mask:0xa bank_mask:0xf
	s_nop 1
	v_add_u32_dpp v73, v73, v73 row_bcast:31 row_mask:0xc bank_mask:0xf
	v_sub_u32_e32 v70, v73, v70
	s_andn2_b64 vcc, exec, s[44:45]
	s_cbranch_vccnz .LBB0_910
	v_cmp_ge_u32_e32 vcc, v6, v69
	s_nop 1
	v_cndmask_b32_e32 v6, v4, v70, vcc
	v_lshl_add_u32 v6, v6, 1, s56
	ds_write_b16 v6, v163
	v_cndmask_b32_e64 v6, 0, 1, vcc
	v_addc_co_u32_e32 v71, vcc, 0, v70, vcc
	v_cmp_ge_u32_e32 vcc, v5, v69
	s_nop 1
	v_cndmask_b32_e32 v5, v4, v71, vcc
	v_lshl_add_u32 v5, v5, 1, s56
	ds_write_b16 v5, v0
	v_cndmask_b32_e64 v5, 0, 1, vcc
	v_addc_co_u32_e32 v6, vcc, v70, v6, vcc
	v_cmp_ge_u32_e32 vcc, v8, v69
	s_nop 1
	v_cndmask_b32_e32 v8, v4, v6, vcc
	v_lshl_add_u32 v8, v8, 1, s56
	ds_write_b16 v8, v2
	v_cndmask_b32_e64 v8, 0, 1, vcc
	v_addc_co_u32_e32 v5, vcc, v71, v5, vcc
	v_cmp_ge_u32_e32 vcc, v7, v69
	s_nop 1
	v_cndmask_b32_e32 v7, v4, v5, vcc
	v_lshl_add_u32 v7, v7, 1, s56
	ds_write_b16 v7, v3
	v_cndmask_b32_e64 v7, 0, 1, vcc
	v_addc_co_u32_e32 v6, vcc, v6, v8, vcc
	v_cmp_ge_u32_e32 vcc, v10, v69
	s_nop 1
	v_cndmask_b32_e32 v8, v4, v6, vcc
	v_lshl_add_u32 v8, v8, 1, s56
	ds_write_b16 v8, v4
	v_cndmask_b32_e64 v8, 0, 1, vcc
	v_addc_co_u32_e32 v5, vcc, v5, v7, vcc
	v_cmp_ge_u32_e32 vcc, v9, v69
	v_or_b32_e32 v7, 0x140, v163
	s_nop 0
	v_cndmask_b32_e32 v9, v4, v5, vcc
	v_lshl_add_u32 v9, v9, 1, s56
	ds_write_b16 v9, v7
	v_cndmask_b32_e64 v7, 0, 1, vcc
	v_addc_co_u32_e32 v6, vcc, v6, v8, vcc
	v_cmp_ge_u32_e32 vcc, v12, v69
	v_or_b32_e32 v8, 0x180, v163
	s_nop 0
	v_cndmask_b32_e32 v9, v4, v6, vcc
	v_lshl_add_u32 v9, v9, 1, s56
	ds_write_b16 v9, v8
	v_cndmask_b32_e64 v8, 0, 1, vcc
	v_addc_co_u32_e32 v5, vcc, v5, v7, vcc
	v_cmp_ge_u32_e32 vcc, v11, v69
	v_or_b32_e32 v7, 0x1c0, v163
	s_nop 0
	v_cndmask_b32_e32 v5, v4, v5, vcc
	v_lshl_add_u32 v5, v5, 1, s56
	v_addc_co_u32_e32 v70, vcc, v6, v8, vcc
	ds_write_b16 v5, v7

; #define LAS __attribute__((address_space(3)))
;     ...
;           for (int jj = 0; jj < 4; ++jj) {
;               const int rho = jj * 16 + c16, slot = b * 64 + rho;
;               f32x4 a = {0.f, 0.f, 0.f, 0.f}; float ss = 0.f;
; #pragma unroll
;               for (int ks = 0; ks < 4; ++ks) {
; #pragma unroll
;                   for (int e = 0; e < 4; ++e) asm("v_dot2_f32_bf16 %0, %1, %1, %0" : "+v"(ss) : "v"(w[jj][ks][e]));
;                   a = __builtin_amdgcn_mfma_f32_16x16x32_bf16(qa[ks], *reinterpret_cast<const bf16x8*>(&w[jj][ks]), a, 0, 0, 0);
;                   *(LAS u32x4*)(wbase + rho * 256 + (((ks * 4 + quad) ^ fsw) << 4)) = w[jj][ks]; }
;               ss += __shfl_xor(ss, 16); ss += __shfl_xor(ss, 32);
;               const float rstd = rsqrtf(ss * (1.f / 128.f) + EPS);
;               const float av = quad == 0 ? a[0] : (quad == 1 ? a[1] : (quad == 2 ? a[2] : a[3]));
;               rsv[jj] = rstd; lgv[jj] = (slot < kcount) ? av * rstd * 0.08838834764831845f : -__builtin_inff();
;           }
.LBB0_928:
	s_add_i32 s0, s24, 1
	s_cmp_ge_i32 s0, s23
	s_cbranch_scc0 .Ldsa_steady
	v_mov_b32_e32 v118, 0
	s_waitcnt vmcnt(13)
	v_dot2_f32_bf16 v118, v26, v26, v118
	v_add_u32_e32 v0, v146, v147
	v_dot2_f32_bf16 v118, v27, v27, v118
	ds_write_b128 v0, v[26:29]
	v_dot2_f32_bf16 v118, v28, v28, v118
	v_add_u32_e32 v0, v146, v148
	v_dot2_f32_bf16 v118, v29, v29, v118
	ds_write_b128 v0, v[18:21]
	v_dot2_f32_bf16 v118, v18, v18, v118
	v_add_u32_e32 v0, v146, v149
	v_dot2_f32_bf16 v118, v19, v19, v118
	ds_write_b128 v0, v[22:25]
	v_dot2_f32_bf16 v118, v20, v20, v118
	v_add_u32_e32 v0, v146, v150
	v_dot2_f32_bf16 v118, v21, v21, v118
	v_and_b32_e32 v119, 64, v206
	v_dot2_f32_bf16 v118, v22, v22, v118
	s_waitcnt vmcnt(12)
	ds_write_b128 v0, v[30:33]
	v_dot2_f32_bf16 v118, v23, v23, v118
	v_dot2_f32_bf16 v118, v24, v24, v118
	v_add_u32_e32 v158, 64, v119
	v_dot2_f32_bf16 v118, v25, v25, v118
	v_dot2_f32_bf16 v118, v30, v30, v118
	v_mfma_f32_16x16x32_bf16 v[114:117], v[2:5], v[26:29], 0
	v_dot2_f32_bf16 v118, v31, v31, v118
	v_dot2_f32_bf16 v118, v32, v32, v118
	v_dot2_f32_bf16 v118, v33, v33, v118
	v_mfma_f32_16x16x32_bf16 v[114:117], v[6:9], v[18:21], v[114:117]
	s_nop 1
	v_mov_b32_e32 v119, v118
	s_nop 1
	v_permlane16_swap_b32_e32 v118, v119
	v_add_f32_e32 v161, v118, v119
	v_xor_b32_e32 v118, 32, v206
	v_mfma_f32_16x16x32_bf16 v[114:117], v[10:13], v[22:25], v[114:117]
	v_cmp_lt_i32_e32 vcc, v118, v158
	s_nop 1
	v_cndmask_b32_e32 v118, v206, v118, vcc
	v_lshlrev_b32_e32 v122, 2, v118
	ds_bpermute_b32 v172, v122, v161
	v_mfma_f32_16x16x32_bf16 v[114:117], v[14:17], v[30:33], v[114:117]
	v_cmp_lt_i32_e32 vcc, 0, v128
	s_and_saveexec_b64 s[0:1], vcc
	s_xor_b64 s[0:1], exec, s[0:1]
	s_cbranch_execz .LBB0_932
	v_cmp_ne_u32_e32 vcc, 1, v128
	s_nop 2
	v_mov_b32_e32 v114, v115
	s_and_saveexec_b64 s[20:21], vcc
	s_xor_b64 s[20:21], exec, s[20:21]
	v_cndmask_b32_e64 v114, v117, v116, s[40:41]
	s_andn2_saveexec_b64 s[20:21], s[20:21]
	s_or_b64 exec, exec, s[20:21]

; #define LAS __attribute__((address_space(3)))
;     ...
;       auto gl = [&](int b) {
; #pragma unroll
;           for (int jj = 0; jj < 4; ++jj) { const int kx = list[(b * 4 + jj) * 16 + c16] & 4095; const u16* cp = prow + (size_t)kx * NP + C_BC + quad * 8;
; #pragma unroll
;               for (int ks = 0; ks < 4; ++ks) w[jj][ks] = *(const u32x4*)(cp + ks * 32); } };
;       if (nb > 0) gl(0);
;       for (int b = 0; b < nb; ++b) {
;           float lgv[4], rsv[4];
; #pragma unroll
;           for (int jj = 0; jj < 4; ++jj) {
;               const int rho = jj * 16 + c16, slot = b * 64 + rho;
;               f32x4 a = {0.f, 0.f, 0.f, 0.f}; float ss = 0.f;
; #pragma unroll
;               for (int ks = 0; ks < 4; ++ks) {
; #pragma unroll
;                   for (int e = 0; e < 4; ++e) asm("v_dot2_f32_bf16 %0, %1, %1, %0" : "+v"(ss) : "v"(w[jj][ks][e]));
;                   a = __builtin_amdgcn_mfma_f32_16x16x32_bf16(qa[ks], *reinterpret_cast<const bf16x8*>(&w[jj][ks]), a, 0, 0, 0);
;                   *(LAS u32x4*)(wbase + rho * 256 + (((ks * 4 + quad) ^ fsw) << 4)) = w[jj][ks]; }
;               ss += __shfl_xor(ss, 16); ss += __shfl_xor(ss, 32);
;               const float rstd = rsqrtf(ss * (1.f / 128.f) + EPS);
;               const float av = quad == 0 ? a[0] : (quad == 1 ? a[1] : (quad == 2 ? a[2] : a[3]));
;               rsv[jj] = rstd; lgv[jj] = (slot < kcount) ? av * rstd * 0.08838834764831845f : -__builtin_inff();
;           }
;           if (b + 1 < nb) gl(b + 1);
.Ldsa_steady:
	ds_read_u16 v232, v154
	ds_read_u16 v234, v154 offset:32
	ds_read_u16 v236, v154 offset:64
	ds_read_u16 v238, v154 offset:96
	v_mov_b32_e32 v240, v124
	v_mov_b32_e32 v241, 0
	v_mov_b32_e32 v233, 0
	v_mov_b32_e32 v235, 0
	v_mov_b32_e32 v237, 0
	v_mov_b32_e32 v239, 0
	s_mov_b64 s[0:1], 0x1000
	v_lshl_add_u64 v[242:243], s[54:55], 0, v[240:241]
	v_lshl_add_u64 v[242:243], v[242:243], 0, s[0:1]
	s_waitcnt lgkmcnt(0)
	v_and_b32_e32 v232, 0xfff, v232
	v_mul_u32_u24_e32 v232, 0x5800, v232
	v_lshl_add_u64 v[224:225], v[232:233], 0, v[242:243]
	v_and_b32_e32 v234, 0xfff, v234
	v_mul_u32_u24_e32 v234, 0x5800, v234
	v_lshl_add_u64 v[226:227], v[234:235], 0, v[242:243]
	v_and_b32_e32 v236, 0xfff, v236
	v_mul_u32_u24_e32 v236, 0x5800, v236
	v_lshl_add_u64 v[228:229], v[236:237], 0, v[242:243]
	v_and_b32_e32 v238, 0xfff, v238
	v_mul_u32_u24_e32 v238, 0x5800, v238
	v_lshl_add_u64 v[230:231], v[238:239], 0, v[242:243]
	v_mov_b32_e32 v118, 0
	s_waitcnt vmcnt(13)
	v_dot2_f32_bf16 v118, v26, v26, v118
	v_add_u32_e32 v0, v146, v147
	v_dot2_f32_bf16 v118, v27, v27, v118
	ds_write_b128 v0, v[26:29]
	v_dot2_f32_bf16 v118, v28, v28, v118
	v_add_u32_e32 v0, v146, v148
	v_dot2_f32_bf16 v118, v29, v29, v118
	ds_write_b128 v0, v[18:21]
	v_dot2_f32_bf16 v118, v18, v18, v118
	v_add_u32_e32 v0, v146, v149
	v_dot2_f32_bf16 v118, v19, v19, v118
	ds_write_b128 v0, v[22:25]
	v_dot2_f32_bf16 v118, v20, v20, v118
	v_add_u32_e32 v0, v146, v150
	v_dot2_f32_bf16 v118, v21, v21, v118
	v_and_b32_e32 v119, 64, v206
	v_dot2_f32_bf16 v118, v22, v22, v118
	s_waitcnt vmcnt(12)
	ds_write_b128 v0, v[30:33]
	v_dot2_f32_bf16 v118, v23, v23, v118
	v_dot2_f32_bf16 v118, v24, v24, v118
	v_add_u32_e32 v158, 64, v119
	v_dot2_f32_bf16 v118, v25, v25, v118
	v_dot2_f32_bf16 v118, v30, v30, v118
	v_mfma_f32_16x16x32_bf16 v[114:117], v[2:5], v[26:29], 0
	v_dot2_f32_bf16 v118, v31, v31, v118
	v_dot2_f32_bf16 v118, v32, v32, v118
	v_dot2_f32_bf16 v118, v33, v33, v118
	v_mfma_f32_16x16x32_bf16 v[114:117], v[6:9], v[18:21], v[114:117]
	s_nop 1
	v_mov_b32_e32 v119, v118
	s_nop 1
	v_permlane16_swap_b32_e32 v118, v119
	v_add_f32_e32 v161, v118, v119
	v_xor_b32_e32 v118, 32, v206
	v_mfma_f32_16x16x32_bf16 v[114:117], v[10:13], v[22:25], v[114:117]
	v_cmp_lt_i32_e32 vcc, v118, v158
	s_nop 1
	v_cndmask_b32_e32 v118, v206, v118, vcc
	v_lshlrev_b32_e32 v122, 2, v118
	ds_bpermute_b32 v172, v122, v161
	v_mfma_f32_16x16x32_bf16 v[114:117], v[14:17], v[30:33], v[114:117]
	global_load_dwordx4 v[18:21], v[224:225], off offset:64
	global_load_dwordx4 v[22:25], v[224:225], off offset:128
	global_load_dwordx4 v[26:29], v[224:225], off
	global_load_dwordx4 v[30:33], v[224:225], off offset:192
	v_cmp_lt_i32_e32 vcc, 0, v128
	s_and_saveexec_b64 s[0:1], vcc
	s_xor_b64 s[0:1], exec, s[0:1]
	s_cbranch_execz .Ldsa_s932
	v_cmp_ne_u32_e32 vcc, 1, v128
	s_nop 2
	v_mov_b32_e32 v114, v115
	s_and_saveexec_b64 s[20:21], vcc
	s_xor_b64 s[20:21], exec, s[20:21]
	v_cndmask_b32_e64 v114, v117, v116, s[40:41]
	s_andn2_saveexec_b64 s[20:21], s[20:21]
	s_or_b64 exec, exec, s[20:21]
.Ldsa_s932:
	s_andn2_saveexec_b64 s[0:1], s[0:1]
	s_or_b64 exec, exec, s[0:1]
	s_nop 1
	v_mov_b32_e32 v115, 0
	s_waitcnt vmcnt(13)
	v_dot2_f32_bf16 v115, v42, v42, v115
	v_mfma_f32_16x16x32_bf16 v[116:119], v[2:5], v[42:45], 0
	v_dot2_f32_bf16 v115, v43, v43, v115
	v_add_u32_e32 v120, v151, v147
	v_dot2_f32_bf16 v115, v44, v44, v115
	ds_write_b128 v120, v[42:45]
	v_dot2_f32_bf16 v115, v45, v45, v115
	v_add_u32_e32 v120, v151, v148
	v_dot2_f32_bf16 v115, v34, v34, v115
	ds_write_b128 v120, v[34:37]
	v_dot2_f32_bf16 v115, v35, v35, v115
	v_add_u32_e32 v120, v151, v149
	v_dot2_f32_bf16 v115, v36, v36, v115
	v_mfma_f32_16x16x32_bf16 v[116:119], v[6:9], v[34:37], v[116:119]
	v_dot2_f32_bf16 v115, v37, v37, v115
	ds_write_b128 v120, v[38:41]
	v_dot2_f32_bf16 v115, v38, v38, v115
	v_add_u32_e32 v120, v151, v150
	v_dot2_f32_bf16 v115, v39, v39, v115
	s_waitcnt vmcnt(12)
	ds_write_b128 v120, v[46:49]
	v_dot2_f32_bf16 v115, v40, v40, v115
	v_mfma_f32_16x16x32_bf16 v[116:119], v[10:13], v[38:41], v[116:119]
	v_dot2_f32_bf16 v115, v41, v41, v115
	v_cmp_lt_i32_e32 vcc, 0, v128
	v_dot2_f32_bf16 v115, v46, v46, v115
	v_mfma_f32_16x16x32_bf16 v[116:119], v[14:17], v[46:49], v[116:119]
	v_dot2_f32_bf16 v115, v47, v47, v115
	s_nop 0
	v_dot2_f32_bf16 v115, v48, v48, v115
	s_nop 0
	v_dot2_f32_bf16 v115, v49, v49, v115
	global_load_dwordx4 v[34:37], v[226:227], off offset:64
	global_load_dwordx4 v[38:41], v[226:227], off offset:128
	global_load_dwordx4 v[42:45], v[226:227], off
	global_load_dwordx4 v[46:49], v[226:227], off offset:192
	s_nop 2
	v_mov_b32_e32 v120, v115
	s_nop 1
	v_permlane16_swap_b32_e32 v115, v120
	v_add_f32_e32 v115, v115, v120
	ds_bpermute_b32 v173, v122, v115
	s_and_saveexec_b64 s[0:1], vcc
	s_xor_b64 s[0:1], exec, s[0:1]
	s_cbranch_execz .Ldsa_s936
	v_cmp_ne_u32_e32 vcc, 1, v128
	v_mov_b32_e32 v116, v117
	s_and_saveexec_b64 s[20:21], vcc
	s_xor_b64 s[20:21], exec, s[20:21]
	v_cndmask_b32_e64 v116, v119, v118, s[40:41]
	s_andn2_saveexec_b64 s[20:21], s[20:21]
	s_or_b64 exec, exec, s[20:21]
; #define LAS __attribute__((address_space(3)))
;     ...
;           for (int jj = 0; jj < 4; ++jj) {
;               const int rho = jj * 16 + c16, slot = b * 64 + rho;
;               f32x4 a = {0.f, 0.f, 0.f, 0.f}; float ss = 0.f;
; #pragma unroll
;               for (int ks = 0; ks < 4; ++ks) {
; #pragma unroll
;                   for (int e = 0; e < 4; ++e) asm("v_dot2_f32_bf16 %0, %1, %1, %0" : "+v"(ss) : "v"(w[jj][ks][e]));
;                   a = __builtin_amdgcn_mfma_f32_16x16x32_bf16(qa[ks], *reinterpret_cast<const bf16x8*>(&w[jj][ks]), a, 0, 0, 0);
;                   *(LAS u32x4*)(wbase + rho * 256 + (((ks * 4 + quad) ^ fsw) << 4)) = w[jj][ks]; }
;               ss += __shfl_xor(ss, 16); ss += __shfl_xor(ss, 32);
;               const float rstd = rsqrtf(ss * (1.f / 128.f) + EPS);
;               const float av = quad == 0 ? a[0] : (quad == 1 ? a[1] : (quad == 2 ? a[2] : a[3]));
;               rsv[jj] = rstd; lgv[jj] = (slot < kcount) ? av * rstd * 0.08838834764831845f : -__builtin_inff();
;           }
;           if (b + 1 < nb) gl(b + 1);
.Ldsa_s936:
	s_andn2_saveexec_b64 s[0:1], s[0:1]
	s_or_b64 exec, exec, s[0:1]
	v_mov_b32_e32 v117, 0
	s_waitcnt vmcnt(13)
	v_dot2_f32_bf16 v117, v58, v58, v117
	v_mfma_f32_16x16x32_bf16 v[118:121], v[2:5], v[58:61], 0
	v_dot2_f32_bf16 v117, v59, v59, v117
	v_add_u32_e32 v123, v152, v147
	v_dot2_f32_bf16 v117, v60, v60, v117
	ds_write_b128 v123, v[58:61]
	v_dot2_f32_bf16 v117, v61, v61, v117
	v_add_u32_e32 v123, v152, v148
	v_dot2_f32_bf16 v117, v50, v50, v117
	ds_write_b128 v123, v[50:53]
	v_dot2_f32_bf16 v117, v51, v51, v117
	v_add_u32_e32 v123, v152, v149
	v_dot2_f32_bf16 v117, v52, v52, v117
	v_mfma_f32_16x16x32_bf16 v[118:121], v[6:9], v[50:53], v[118:121]
	v_dot2_f32_bf16 v117, v53, v53, v117
	ds_write_b128 v123, v[54:57]
	v_dot2_f32_bf16 v117, v54, v54, v117
	v_add_u32_e32 v123, v152, v150
	v_dot2_f32_bf16 v117, v55, v55, v117
	s_waitcnt vmcnt(12)
	ds_write_b128 v123, v[62:65]
	v_dot2_f32_bf16 v117, v56, v56, v117
	v_mfma_f32_16x16x32_bf16 v[118:121], v[10:13], v[54:57], v[118:121]
	v_dot2_f32_bf16 v117, v57, v57, v117
	v_cmp_lt_i32_e32 vcc, 0, v128
	v_dot2_f32_bf16 v117, v62, v62, v117
	v_mfma_f32_16x16x32_bf16 v[118:121], v[14:17], v[62:65], v[118:121]
	v_dot2_f32_bf16 v117, v63, v63, v117
	s_nop 0
	v_dot2_f32_bf16 v117, v64, v64, v117
	s_nop 0
	v_dot2_f32_bf16 v117, v65, v65, v117
	global_load_dwordx4 v[50:53], v[228:229], off offset:64
	global_load_dwordx4 v[54:57], v[228:229], off offset:128
	global_load_dwordx4 v[58:61], v[228:229], off
	global_load_dwordx4 v[62:65], v[228:229], off offset:192
	s_nop 2
	v_mov_b32_e32 v123, v117
	s_nop 1
	v_permlane16_swap_b32_e32 v117, v123
	v_add_f32_e32 v117, v117, v123
	ds_bpermute_b32 v174, v122, v117
	s_and_saveexec_b64 s[0:1], vcc
	s_xor_b64 s[0:1], exec, s[0:1]
	s_cbranch_execz .Ldsa_s940
	v_cmp_ne_u32_e32 vcc, 1, v128
	v_mov_b32_e32 v118, v119
	s_and_saveexec_b64 s[20:21], vcc
	s_xor_b64 s[20:21], exec, s[20:21]
	v_cndmask_b32_e64 v118, v121, v120, s[40:41]
	s_andn2_saveexec_b64 s[20:21], s[20:21]
	s_or_b64 exec, exec, s[20:21]
.Ldsa_s940:
	s_andn2_saveexec_b64 s[0:1], s[0:1]
	s_or_b64 exec, exec, s[0:1]
	v_mov_b32_e32 v119, 0
	s_waitcnt vmcnt(13)
	v_dot2_f32_bf16 v119, v74, v74, v119
	v_mfma_f32_16x16x32_bf16 v[176:179], v[2:5], v[74:77], 0
	v_dot2_f32_bf16 v119, v75, v75, v119
	v_add_u32_e32 v120, v153, v147
	v_dot2_f32_bf16 v119, v76, v76, v119
	v_mfma_f32_16x16x32_bf16 v[176:179], v[6:9], v[66:69], v[176:179]
	v_dot2_f32_bf16 v119, v77, v77, v119
	ds_write_b128 v120, v[74:77]
	v_dot2_f32_bf16 v119, v66, v66, v119
	v_mfma_f32_16x16x32_bf16 v[176:179], v[10:13], v[70:73], v[176:179]
	v_dot2_f32_bf16 v119, v67, v67, v119
	v_add_u32_e32 v120, v153, v148
	v_dot2_f32_bf16 v119, v68, v68, v119
	ds_write_b128 v120, v[66:69]
	v_dot2_f32_bf16 v119, v69, v69, v119
	v_add_u32_e32 v120, v153, v149
	v_dot2_f32_bf16 v119, v70, v70, v119
	ds_write_b128 v120, v[70:73]
	v_dot2_f32_bf16 v119, v71, v71, v119
	v_cmp_lt_i32_e32 vcc, 0, v128
	v_dot2_f32_bf16 v119, v72, v72, v119
	s_nop 0
	v_dot2_f32_bf16 v119, v73, v73, v119
	s_waitcnt vmcnt(12)
	v_dot2_f32_bf16 v119, v78, v78, v119
	s_nop 0
	v_dot2_f32_bf16 v119, v79, v79, v119
	s_nop 0
	v_dot2_f32_bf16 v119, v80, v80, v119
	s_nop 0
	v_dot2_f32_bf16 v119, v81, v81, v119
	s_nop 2
	v_mov_b32_e32 v0, v119
	s_nop 1
	v_permlane16_swap_b32_e32 v119, v0
	v_add_f32_e32 v119, v119, v0
	ds_bpermute_b32 v175, v122, v119
	v_mfma_f32_16x16x32_bf16 v[120:123], v[14:17], v[78:81], v[176:179]
	v_add_u32_e32 v0, v153, v150
	ds_write_b128 v0, v[78:81]
	global_load_dwordx4 v[66:69], v[230:231], off offset:64
	global_load_dwordx4 v[70:73], v[230:231], off offset:128
	global_load_dwordx4 v[74:77], v[230:231], off
	global_load_dwordx4 v[78:81], v[230:231], off offset:192
	s_and_saveexec_b64 s[0:1], vcc
	s_xor_b64 s[0:1], exec, s[0:1]
	s_cbranch_execz .Ldsa_s944
	v_cmp_ne_u32_e32 vcc, 1, v128
	s_nop 1
	v_mov_b32_e32 v120, v121
	s_and_saveexec_b64 s[20:21], vcc
	s_xor_b64 s[20:21], exec, s[20:21]
	v_cndmask_b32_e64 v120, v123, v122, s[40:41]
	s_andn2_saveexec_b64 s[20:21], s[20:21]
	s_or_b64 exec, exec, s[20:21]
.Ldsa_s944:
	s_andn2_saveexec_b64 s[0:1], s[0:1]
	s_or_b64 exec, exec, s[0:1]
	s_add_i32 s24, s24, 1
	s_branch .LBB0_946

; #define LAS __attribute__((address_space(3)))
;     ...
; #pragma unroll
;       for (int o = 1; o < 16; o <<= 1) lsum += __shfl_xor(lsum, o);
;       if (c16 == 0) alf[quad] = 1.f / lsum;
;       const f32x4 il4 = *(const LAS f32x4*)alf;
.LBB0_953:
	s_nop 1
	v_add_f32_dpp v0, v118, v118 quad_perm:[1,0,3,2] row_mask:0xf bank_mask:0xf
	s_nop 1
	v_add_f32_dpp v0, v0, v0 quad_perm:[2,3,0,1] row_mask:0xf bank_mask:0xf
	s_nop 1
	v_add_f32_dpp v0, v0, v0 row_half_mirror row_mask:0xf bank_mask:0xf
	s_nop 1
	v_mov_b32_dpp v2, v0 row_mirror row_mask:0xf bank_mask:0xf
	v_cmp_eq_u32_e32 vcc, 0, v127
	s_and_saveexec_b64 s[0:1], vcc
	s_cbranch_execz .LBB0_955
	s_waitcnt lgkmcnt(0)
	v_add_f32_e32 v0, v0, v2
	v_div_scale_f32 v2, s[20:21], v0, v0, 1.0
	v_rcp_f32_e32 v3, v2
	v_div_scale_f32 v4, vcc, 1.0, v0, 1.0
	v_fma_f32 v5, -v2, v3, 1.0
	v_fmac_f32_e32 v3, v5, v3
	v_mul_f32_e32 v5, v4, v3
	v_fma_f32 v6, -v2, v5, v4
	v_fmac_f32_e32 v5, v6, v3
	v_fma_f32 v2, -v2, v5, v4
	v_div_fmas_f32 v2, v2, v3, v5
	v_div_fixup_f32 v0, v2, v0, 1.0
	ds_write_b32 v129, v0 offset:640

; __device__ __forceinline__ unsigned cvtpk(float lo, float hi) { unsigned r; asm volatile("v_cvt_pk_bf16_f32 %0, %1, %2" : "=v"(r) : "v"(lo), "v"(hi)); return r; }
; __device__ __forceinline__ void item_fox(const Params& p, int l, int bl, int h, int qb, LAS unsigned char* lds) {
;     ...
;         float mx = S0[0];
; #pragma unroll
;         for (int r = 1; r < 16; ++r) mx = fmaxf(mx, S0[r]);
; #pragma unroll
;         for (int r = 0; r < 16; ++r) mx = fmaxf(mx, S1[r]);
;         mx = fmaxf(mx, __shfl_xor(mx, 32));
;         const float mnew = fmaxf(mrun, mx), alpha = __builtin_amdgcn_exp2f(mrun - mnew); mrun = mnew;
;         float ps = 0.f;
; #pragma unroll
;         for (int r = 0; r < 16; ++r) { S0[r] = __builtin_amdgcn_exp2f(S0[r] - mnew); S1[r] = __builtin_amdgcn_exp2f(S1[r] - mnew); ps += S0[r] + S1[r]; }
;         lrun = lrun * alpha + ps;
; #pragma unroll
;         for (int i = 0; i < 4; ++i) O[i] *= alpha;
; #pragma unroll
;         for (int j = 0; j < 2; ++j)
; #pragma unroll
;             for (int e = 0; e < 4; ++e) { Pk[j][e] = cvtpk(S0[8 * j + 2 * e], S0[8 * j + 2 * e + 1]); Pk[2 + j][e] = cvtpk(S1[8 * j + 2 * e], S1[8 * j + 2 * e + 1]); }
.LBB0_1007:
	v_max_f32_e32 v0, v97, v97
	v_max_f32_e32 v90, v96, v96
	v_max_f32_e32 v0, v90, v0
	v_max3_f32 v0, v0, v98, v99
	v_max3_f32 v0, v0, v100, v101
	v_max3_f32 v0, v0, v102, v103
	v_max3_f32 v0, v0, v12, v13
	v_max3_f32 v0, v0, v8, v9
	v_max3_f32 v0, v0, v4, v5
	v_max3_f32 v0, v0, v2, v3
	v_max3_f32 v0, v0, v80, v81
	v_max3_f32 v0, v0, v82, v83
	v_max3_f32 v0, v0, v84, v85
	v_max3_f32 v0, v0, v86, v87
	v_max3_f32 v0, v0, v88, v89
	v_max3_f32 v0, v0, v14, v15
	v_max3_f32 v0, v0, v10, v11
	v_max3_f32 v0, v0, v6, v7
	v_mov_b32_e32 v90, v0
	s_nop 1
	v_permlane32_swap_b32_e32 v0, v90
	v_max3_f32 v106, v196, v0, v90
	v_sub_f32_e32 v90, v96, v106
	v_sub_f32_e32 v80, v80, v106
	v_exp_f32_e32 v92, v90
	v_exp_f32_e32 v93, v80
	v_sub_f32_e32 v80, v97, v106
	v_sub_f32_e32 v81, v81, v106
	v_exp_f32_e32 v94, v80
	v_exp_f32_e32 v95, v81
	v_sub_f32_e32 v81, v98, v106
	v_add_f32_e32 v80, v92, v93
	v_exp_f32_e32 v107, v81
	v_sub_f32_e32 v81, v82, v106
	v_exp_f32_e32 v108, v81
	v_add_f32_e32 v80, 0, v80
	v_add_f32_e32 v81, v94, v95
	v_add_f32_e32 v90, v81, v80
	v_sub_f32_e32 v80, v99, v106
	v_exp_f32_e32 v109, v80
	v_sub_f32_e32 v80, v83, v106
	v_exp_f32_e32 v110, v80
	v_sub_f32_e32 v80, v100, v106
	v_exp_f32_e32 v81, v80
	v_sub_f32_e32 v80, v84, v106
	v_exp_f32_e32 v83, v80
	v_sub_f32_e32 v80, v101, v106
	v_sub_f32_e32 v82, v85, v106
	v_exp_f32_e32 v80, v80
	v_exp_f32_e32 v82, v82
	v_add_f32_e32 v91, v107, v108
	v_add_f32_e32 v84, v91, v90
	v_add_f32_e32 v85, v109, v110
	v_add_f32_e32 v90, v85, v84
	v_pk_add_f32 v[84:85], v[80:81], v[82:83]
	v_sub_f32_e32 v12, v12, v106
	v_add_f32_e32 v85, v85, v90
	v_add_f32_e32 v84, v84, v85
	v_sub_f32_e32 v85, v102, v106
	v_exp_f32_e32 v97, v85
	v_sub_f32_e32 v85, v86, v106
	v_exp_f32_e32 v91, v85
	v_sub_f32_e32 v85, v103, v106
	v_exp_f32_e32 v96, v85
	v_sub_f32_e32 v85, v87, v106
	v_exp_f32_e32 v99, v12
	v_sub_f32_e32 v12, v88, v106
	v_exp_f32_e32 v90, v85
	v_exp_f32_e32 v101, v12
	v_sub_f32_e32 v12, v13, v106
	v_exp_f32_e32 v98, v12
	v_sub_f32_e32 v12, v89, v106
	v_exp_f32_e32 v100, v12
	v_pk_add_f32 v[12:13], v[96:97], v[90:91]
	v_sub_f32_e32 v8, v8, v106
	v_add_f32_e32 v13, v13, v84
	v_add_f32_e32 v84, v12, v13
	v_pk_add_f32 v[12:13], v[98:99], v[100:101]
	v_sub_f32_e32 v4, v4, v106
	v_add_f32_e32 v13, v13, v84
	v_add_f32_e32 v84, v12, v13
	v_exp_f32_e32 v13, v8
	v_sub_f32_e32 v8, v14, v106
	v_exp_f32_e32 v103, v8
	v_sub_f32_e32 v8, v9, v106
	v_exp_f32_e32 v12, v8
	v_sub_f32_e32 v8, v15, v106
	v_exp_f32_e32 v9, v4
	v_sub_f32_e32 v4, v10, v106
	v_exp_f32_e32 v102, v8
	v_exp_f32_e32 v15, v4
	v_sub_f32_e32 v4, v5, v106
	v_sub_f32_e32 v2, v2, v106
	v_exp_f32_e32 v8, v4
	v_sub_f32_e32 v4, v11, v106
	v_exp_f32_e32 v11, v2
	v_sub_f32_e32 v2, v6, v106
	v_exp_f32_e32 v14, v4
	v_exp_f32_e32 v105, v2
	v_sub_f32_e32 v2, v3, v106
	v_exp_f32_e32 v10, v2
	v_sub_f32_e32 v2, v7, v106
	v_pk_add_f32 v[4:5], v[12:13], v[102:103]
	v_exp_f32_e32 v104, v2
	v_add_f32_e32 v5, v5, v84
	v_sub_f32_e32 v0, v196, v106
	v_add_f32_e32 v84, v4, v5
	v_pk_add_f32 v[4:5], v[8:9], v[14:15]
	v_exp_f32_e32 v0, v0
	v_add_f32_e32 v2, v5, v84
	v_add_f32_e32 v4, v4, v2
	v_pk_add_f32 v[2:3], v[10:11], v[104:105]
	v_pk_mul_f32 v[78:79], v[78:79], v[0:1] op_sel_hi:[1,0]
	v_add_f32_e32 v3, v3, v4
	v_add_f32_e32 v2, v2, v3
	v_fmac_f32_e32 v2, v187, v0
	v_pk_mul_f32 v[76:77], v[76:77], v[0:1] op_sel_hi:[1,0]
	v_pk_mul_f32 v[74:75], v[74:75], v[0:1] op_sel_hi:[1,0]
	v_pk_mul_f32 v[72:73], v[72:73], v[0:1] op_sel_hi:[1,0]
	v_pk_mul_f32 v[70:71], v[70:71], v[0:1] op_sel_hi:[1,0]
	v_pk_mul_f32 v[68:69], v[68:69], v[0:1] op_sel_hi:[1,0]
	v_pk_mul_f32 v[66:67], v[66:67], v[0:1] op_sel_hi:[1,0]
	v_pk_mul_f32 v[64:65], v[64:65], v[0:1] op_sel_hi:[1,0]
	v_pk_mul_f32 v[62:63], v[62:63], v[0:1] op_sel_hi:[1,0]
	v_pk_mul_f32 v[60:61], v[60:61], v[0:1] op_sel_hi:[1,0]
	v_pk_mul_f32 v[58:59], v[58:59], v[0:1] op_sel_hi:[1,0]
	v_pk_mul_f32 v[56:57], v[56:57], v[0:1] op_sel_hi:[1,0]
	v_pk_mul_f32 v[54:55], v[54:55], v[0:1] op_sel_hi:[1,0]
	v_pk_mul_f32 v[52:53], v[52:53], v[0:1] op_sel_hi:[1,0]
	v_pk_mul_f32 v[50:51], v[50:51], v[0:1] op_sel_hi:[1,0]
	v_pk_mul_f32 v[48:49], v[48:49], v[0:1] op_sel_hi:[1,0]
	v_pk_mul_f32 v[46:47], v[46:47], v[0:1] op_sel_hi:[1,0]
	v_pk_mul_f32 v[44:45], v[44:45], v[0:1] op_sel_hi:[1,0]
	v_pk_mul_f32 v[42:43], v[42:43], v[0:1] op_sel_hi:[1,0]
	v_pk_mul_f32 v[40:41], v[40:41], v[0:1] op_sel_hi:[1,0]
	v_pk_mul_f32 v[38:39], v[38:39], v[0:1] op_sel_hi:[1,0]
	v_pk_mul_f32 v[36:37], v[36:37], v[0:1] op_sel_hi:[1,0]
	v_pk_mul_f32 v[34:35], v[34:35], v[0:1] op_sel_hi:[1,0]
	v_pk_mul_f32 v[32:33], v[32:33], v[0:1] op_sel_hi:[1,0]
	v_pk_mul_f32 v[30:31], v[30:31], v[0:1] op_sel_hi:[1,0]
	v_pk_mul_f32 v[28:29], v[28:29], v[0:1] op_sel_hi:[1,0]
	v_pk_mul_f32 v[26:27], v[26:27], v[0:1] op_sel_hi:[1,0]
	v_pk_mul_f32 v[24:25], v[24:25], v[0:1] op_sel_hi:[1,0]
	v_pk_mul_f32 v[22:23], v[22:23], v[0:1] op_sel_hi:[1,0]
	v_pk_mul_f32 v[20:21], v[20:21], v[0:1] op_sel_hi:[1,0]
	v_pk_mul_f32 v[18:19], v[18:19], v[0:1] op_sel_hi:[1,0]
	v_pk_mul_f32 v[16:17], v[16:17], v[0:1] op_sel_hi:[1,0]
	v_mov_b32_e32 v187, v2
	v_mov_b32_e32 v196, v106
	v_cvt_pk_bf16_f32 v92, v92, v94
	v_cvt_pk_bf16_f32 v84, v93, v95
	v_cvt_pk_bf16_f32 v93, v107, v109
	v_cvt_pk_bf16_f32 v85, v108, v110
	v_cvt_pk_bf16_f32 v94, v81, v80
	v_cvt_pk_bf16_f32 v86, v83, v82
	v_cvt_pk_bf16_f32 v95, v97, v96
	v_cvt_pk_bf16_f32 v87, v91, v90
	v_cvt_pk_bf16_f32 v88, v99, v98
	v_cvt_pk_bf16_f32 v80, v101, v100
	v_cvt_pk_bf16_f32 v89, v13, v12
	v_cvt_pk_bf16_f32 v81, v103, v102
	v_cvt_pk_bf16_f32 v90, v9, v8
	v_cvt_pk_bf16_f32 v82, v15, v14
	v_cvt_pk_bf16_f32 v91, v11, v10
	v_cvt_pk_bf16_f32 v83, v105, v104
	s_and_b64 s[0:1], s[28:29], s[44:45]
	s_andn2_b64 vcc, exec, s[0:1]
	s_cbranch_vccnz .LBB0_1001
